# gMLP output block: bf16 conversions write straight into the store holding quads (64 v_mov per unit removed)
# speedup vs baseline: 1.0069x; 1.0009x over previous
; #define LAS __attribute__((address_space(3)))
; __device__ __forceinline__ unsigned pk2(float lo, float hi) { f32x2 v = {lo, hi}; bf16x2_t b = __builtin_convertvector(v, bf16x2_t); return __builtin_bit_cast(unsigned, b); }
; __device__ __forceinline__ void gmlp_unit(const GmlpP& P, int b, int ch, LAS unsigned char* lds, int wave, int lane_in) {
;     ...
;     __syncthreads();
; #pragma unroll
;     for (int nt = 0; nt < 2; ++nt) {
;         const int t = 32 * (nt == 0 ? tt0 : tt1) + r32;
;         const float tot = (ssqg[t] + ssqg[128 + t]) + (ssqg[256 + t] + ssqg[384 + t]);
;         const float r = __builtin_amdgcn_rsqf(tot * (1.0f / GW) + EPS);
;         bf16_t* op = P.MIX + (tok0 + t) * DM + AW + gI * 128 + 4 * h;
; #pragma unroll
;         for (int mt = 0; mt < 4; ++mt)
; #pragma unroll
;             for (int e4 = 0; e4 < 4; ++e4) {
;                 const f32x4 gg = *(const LAS f32x4*)(lds + LDS_GG + (gI * 128 + 32 * mt + 8 * e4 + 4 * h) * 4);
;                 u32x2 w; w.x = pk2(acc[mt][nt][4 * e4] * r * gg[0], acc[mt][nt][4 * e4 + 1] * r * gg[1]); w.y = pk2(acc[mt][nt][4 * e4 + 2] * r * gg[2], acc[mt][nt][4 * e4 + 3] * r * gg[3]);
;                 *(u32x2*)(op + 32 * mt + 8 * e4) = w;
;             }
;     }
.LBB0_536:
	s_or_b64 exec, exec, s[26:27]
	s_add_i32 s18, 0, 0x22000
	v_lshl_add_u32 v4, v157, 2, s18
	s_waitcnt lgkmcnt(0)
	s_barrier
	ds_read2st64_b32 v[2:3], v4 offset1:2
	ds_read2st64_b32 v[4:5], v4 offset0:4 offset1:6
	v_add_u32_e32 v6, s28, v144
	s_add_i32 s26, 0, 0x22800
	v_lshl_add_u32 v153, v6, 2, s26
	s_waitcnt lgkmcnt(1)
	v_mov_b32_e32 v6, v2
	s_waitcnt lgkmcnt(0)
	v_mov_b32_e32 v7, v4
	v_mov_b32_e32 v4, v3
	v_pk_add_f32 v[2:3], v[6:7], v[4:5]
	v_lshlrev_b32_e32 v140, 11, v156
	v_add_f32_e32 v2, v2, v3
	v_fmamk_f32 v2, v2, 0x3b000000, v1
	v_add_u32_e32 v4, s6, v144
	v_rsq_f32_e32 v152, v2
	v_lshl_add_u64 v[2:3], s[16:17], 0, v[140:141]
	v_lshl_add_u32 v140, v4, 2, s26
	ds_read_b128 v[6:9], v140
	v_lshlrev_b64 v[150:151], 1, v[144:145]
	v_lshl_add_u64 v[154:155], v[2:3], 0, v[150:151]
	ds_read_b128 v[2:5], v140 offset:32
	v_pk_mul_f32 v[10:11], v[114:115], v[152:153] op_sel_hi:[1,0]
	v_pk_mul_f32 v[12:13], v[116:117], v[152:153] op_sel_hi:[1,0]
	s_waitcnt lgkmcnt(1)
	v_pk_mul_f32 v[10:11], v[6:7], v[10:11]
	v_pk_mul_f32 v[12:13], v[8:9], v[12:13]
	v_cvt_pk_bf16_f32 v202, v10, v11
	v_cvt_pk_bf16_f32 v203, v12, v13
	v_and_b32_e32 v222, 32, v0
	v_lshrrev_b32_e32 v222, 2, v222
	v_mov_b32_e32 v223, 0
	v_lshl_add_u64 v[218:219], v[154:155], 0, v[222:223]
	v_pk_mul_f32 v[10:11], v[118:119], v[152:153] op_sel_hi:[1,0]
	v_pk_mul_f32 v[118:119], v[122:123], v[152:153] op_sel_hi:[1,0]
	s_waitcnt lgkmcnt(0)
	v_pk_mul_f32 v[10:11], v[2:3], v[10:11]
	v_pk_mul_f32 v[120:121], v[120:121], v[152:153] op_sel_hi:[1,0]
	v_cvt_pk_bf16_f32 v204, v10, v11
	v_pk_mul_f32 v[10:11], v[130:131], v[152:153] op_sel_hi:[1,0]
	v_pk_mul_f32 v[98:99], v[98:99], v[152:153] op_sel_hi:[1,0]
	v_pk_mul_f32 v[116:117], v[4:5], v[10:11]
	ds_read_b128 v[10:13], v140 offset:64
	v_cvt_pk_bf16_f32 v205, v116, v117
	s_nop 1
	v_permlane32_swap_b32_e32 v202, v204
	v_permlane32_swap_b32_e32 v203, v205
	global_store_dwordx4 v[218:219], v[202:205], off offset:1024
	ds_read_b128 v[114:117], v140 offset:96
	v_pk_mul_f32 v[100:101], v[100:101], v[152:153] op_sel_hi:[1,0]
	s_waitcnt lgkmcnt(1)
	v_pk_mul_f32 v[118:119], v[10:11], v[118:119]
	v_pk_mul_f32 v[120:121], v[12:13], v[120:121]
	v_cvt_pk_bf16_f32 v206, v118, v119
	v_cvt_pk_bf16_f32 v207, v120, v121
	v_pk_mul_f32 v[118:119], v[124:125], v[152:153] op_sel_hi:[1,0]
	v_pk_mul_f32 v[104:105], v[104:105], v[152:153] op_sel_hi:[1,0]
	s_waitcnt lgkmcnt(0)
	v_pk_mul_f32 v[118:119], v[118:119], v[114:115]
	v_pk_mul_f32 v[82:83], v[82:83], v[152:153] op_sel_hi:[1,0]
	v_cvt_pk_bf16_f32 v208, v118, v119
	v_pk_mul_f32 v[118:119], v[126:127], v[152:153] op_sel_hi:[1,0]
	v_pk_mul_f32 v[84:85], v[84:85], v[152:153] op_sel_hi:[1,0]
	v_pk_mul_f32 v[124:125], v[118:119], v[116:117]
	v_add_u32_e32 v118, s29, v144
	v_lshl_add_u32 v130, v118, 2, s26
	ds_read_b128 v[118:121], v130
	v_cvt_pk_bf16_f32 v209, v124, v125
	s_nop 1
	v_permlane32_swap_b32_e32 v206, v208
	v_permlane32_swap_b32_e32 v207, v209
	global_store_dwordx4 v[218:219], v[206:209], off offset:1056
	ds_read_b128 v[122:125], v130 offset:32
	v_pk_mul_f32 v[88:89], v[88:89], v[152:153] op_sel_hi:[1,0]
	s_waitcnt lgkmcnt(1)
	v_pk_mul_f32 v[98:99], v[98:99], v[118:119]
	v_pk_mul_f32 v[100:101], v[100:101], v[120:121]
	v_cvt_pk_bf16_f32 v210, v98, v99
	v_cvt_pk_bf16_f32 v211, v100, v101
	v_pk_mul_f32 v[98:99], v[102:103], v[152:153] op_sel_hi:[1,0]
	v_pk_mul_f32 v[66:67], v[66:67], v[152:153] op_sel_hi:[1,0]
	s_waitcnt lgkmcnt(0)
	v_pk_mul_f32 v[98:99], v[98:99], v[122:123]
	v_pk_mul_f32 v[68:69], v[68:69], v[152:153] op_sel_hi:[1,0]
	v_cvt_pk_bf16_f32 v212, v98, v99
	v_pk_mul_f32 v[98:99], v[128:129], v[152:153] op_sel_hi:[1,0]
	v_pk_mul_f32 v[72:73], v[72:73], v[152:153] op_sel_hi:[1,0]
	v_pk_mul_f32 v[126:127], v[98:99], v[124:125]
	ds_read_b128 v[98:101], v130 offset:64
	v_cvt_pk_bf16_f32 v213, v126, v127
	ds_read_b128 v[126:129], v130 offset:96
	s_nop 1
	v_permlane32_swap_b32_e32 v210, v212
	v_permlane32_swap_b32_e32 v211, v213
	global_store_dwordx4 v[218:219], v[210:213], off offset:1088
	v_pk_mul_f32 v[102:103], v[106:107], v[152:153] op_sel_hi:[1,0]
	s_waitcnt lgkmcnt(1)
	v_pk_mul_f32 v[104:105], v[104:105], v[100:101]
	v_pk_mul_f32 v[102:103], v[102:103], v[98:99]
	v_lshlrev_b32_e32 v140, 11, v139
	v_cvt_pk_bf16_f32 v214, v102, v103
	v_cvt_pk_bf16_f32 v215, v104, v105
	v_pk_mul_f32 v[102:103], v[108:109], v[152:153] op_sel_hi:[1,0]
	s_add_i32 s49, s49, s100
	s_waitcnt lgkmcnt(0)
	v_pk_mul_f32 v[102:103], v[102:103], v[126:127]
	s_add_i32 s38, s38, s39
	v_cvt_pk_bf16_f32 v216, v102, v103
	v_pk_mul_f32 v[102:103], v[110:111], v[152:153] op_sel_hi:[1,0]
	s_cmp_gt_i32 s49, s101
	v_pk_mul_f32 v[108:109], v[102:103], v[128:129]
	v_add_u32_e32 v102, s30, v144
	v_lshl_add_u32 v130, v102, 2, s26
	ds_read_b128 v[102:105], v130
	v_cvt_pk_bf16_f32 v217, v108, v109
	s_nop 1
	v_permlane32_swap_b32_e32 v214, v216
	v_permlane32_swap_b32_e32 v215, v217
	global_store_dwordx4 v[218:219], v[214:217], off offset:1120
	ds_read_b128 v[106:109], v130 offset:32
	s_waitcnt lgkmcnt(1)
	v_pk_mul_f32 v[82:83], v[82:83], v[102:103]
	v_pk_mul_f32 v[84:85], v[84:85], v[104:105]
	v_cvt_pk_bf16_f32 v202, v82, v83
	v_cvt_pk_bf16_f32 v203, v84, v85
	v_pk_mul_f32 v[82:83], v[86:87], v[152:153] op_sel_hi:[1,0]
	s_waitcnt lgkmcnt(0)
	v_pk_mul_f32 v[82:83], v[82:83], v[106:107]
	s_nop 0
	v_cvt_pk_bf16_f32 v204, v82, v83
	v_pk_mul_f32 v[82:83], v[112:113], v[152:153] op_sel_hi:[1,0]
	s_nop 0
	v_pk_mul_f32 v[110:111], v[82:83], v[108:109]
	ds_read_b128 v[82:85], v130 offset:64
	v_cvt_pk_bf16_f32 v205, v110, v111
	ds_read_b128 v[110:113], v130 offset:96
	s_nop 1
	v_permlane32_swap_b32_e32 v202, v204
	v_permlane32_swap_b32_e32 v203, v205
	global_store_dwordx4 v[218:219], v[202:205], off offset:1152
	v_pk_mul_f32 v[86:87], v[90:91], v[152:153] op_sel_hi:[1,0]
	s_waitcnt lgkmcnt(1)
; #define LAS __attribute__((address_space(3)))
; __device__ __forceinline__ unsigned pk2(float lo, float hi) { f32x2 v = {lo, hi}; bf16x2_t b = __builtin_convertvector(v, bf16x2_t); return __builtin_bit_cast(unsigned, b); }
; __device__ __forceinline__ void gmlp_unit(const GmlpP& P, int b, int ch, LAS unsigned char* lds, int wave, int lane_in) {
;     ...
;     for (int nt = 0; nt < 2; ++nt) {
;         const int t = 32 * (nt == 0 ? tt0 : tt1) + r32;
;         const float tot = (ssqg[t] + ssqg[128 + t]) + (ssqg[256 + t] + ssqg[384 + t]);
;         const float r = __builtin_amdgcn_rsqf(tot * (1.0f / GW) + EPS);
;         bf16_t* op = P.MIX + (tok0 + t) * DM + AW + gI * 128 + 4 * h;
; #pragma unroll
;         for (int mt = 0; mt < 4; ++mt)
; #pragma unroll
;             for (int e4 = 0; e4 < 4; ++e4) {
;                 const f32x4 gg = *(const LAS f32x4*)(lds + LDS_GG + (gI * 128 + 32 * mt + 8 * e4 + 4 * h) * 4);
;                 u32x2 w; w.x = pk2(acc[mt][nt][4 * e4] * r * gg[0], acc[mt][nt][4 * e4 + 1] * r * gg[1]); w.y = pk2(acc[mt][nt][4 * e4 + 2] * r * gg[2], acc[mt][nt][4 * e4 + 3] * r * gg[3]);
;                 *(u32x2*)(op + 32 * mt + 8 * e4) = w;
;             }
;     }
	v_pk_mul_f32 v[88:89], v[88:89], v[84:85]
	v_pk_mul_f32 v[86:87], v[86:87], v[82:83]
	s_nop 0
	v_cvt_pk_bf16_f32 v206, v86, v87
	v_cvt_pk_bf16_f32 v207, v88, v89
	v_pk_mul_f32 v[86:87], v[92:93], v[152:153] op_sel_hi:[1,0]
	s_waitcnt lgkmcnt(0)
	v_pk_mul_f32 v[86:87], v[86:87], v[110:111]
	s_nop 0
	v_cvt_pk_bf16_f32 v208, v86, v87
	v_pk_mul_f32 v[86:87], v[94:95], v[152:153] op_sel_hi:[1,0]
	s_nop 0
	v_pk_mul_f32 v[92:93], v[86:87], v[112:113]
	ds_read_b128 v[86:89], v153
	v_cvt_pk_bf16_f32 v209, v92, v93
	s_nop 1
	v_permlane32_swap_b32_e32 v206, v208
	v_permlane32_swap_b32_e32 v207, v209
	global_store_dwordx4 v[218:219], v[206:209], off offset:1184
	ds_read_b128 v[90:93], v153 offset:32
	s_waitcnt lgkmcnt(1)
	v_pk_mul_f32 v[66:67], v[66:67], v[86:87]
	v_pk_mul_f32 v[68:69], v[68:69], v[88:89]
	v_cvt_pk_bf16_f32 v210, v66, v67
	v_cvt_pk_bf16_f32 v211, v68, v69
	v_pk_mul_f32 v[66:67], v[70:71], v[152:153] op_sel_hi:[1,0]
	s_waitcnt lgkmcnt(0)
	v_pk_mul_f32 v[66:67], v[66:67], v[90:91]
	s_nop 0
	v_cvt_pk_bf16_f32 v212, v66, v67
	v_pk_mul_f32 v[66:67], v[96:97], v[152:153] op_sel_hi:[1,0]
	s_nop 0
	v_pk_mul_f32 v[94:95], v[66:67], v[92:93]
	ds_read_b128 v[66:69], v153 offset:64
	v_cvt_pk_bf16_f32 v213, v94, v95
	ds_read_b128 v[94:97], v153 offset:96
	s_nop 1
	v_permlane32_swap_b32_e32 v210, v212
	v_permlane32_swap_b32_e32 v211, v213
	global_store_dwordx4 v[218:219], v[210:213], off offset:1216
	v_pk_mul_f32 v[70:71], v[74:75], v[152:153] op_sel_hi:[1,0]
	s_waitcnt lgkmcnt(1)
	v_pk_mul_f32 v[72:73], v[72:73], v[68:69]
	v_pk_mul_f32 v[70:71], v[70:71], v[66:67]
	s_nop 0
	v_cvt_pk_bf16_f32 v214, v70, v71
	v_cvt_pk_bf16_f32 v215, v72, v73
	v_pk_mul_f32 v[70:71], v[76:77], v[152:153] op_sel_hi:[1,0]
	v_pk_mul_f32 v[72:73], v[78:79], v[152:153] op_sel_hi:[1,0]
	s_waitcnt lgkmcnt(0)
	v_pk_mul_f32 v[70:71], v[70:71], v[94:95]
	v_pk_mul_f32 v[72:73], v[72:73], v[96:97]
	v_cvt_pk_bf16_f32 v216, v70, v71
	v_lshl_add_u32 v71, v158, 2, s18
	ds_read2st64_b32 v[74:75], v71 offset1:2
	ds_read2st64_b32 v[76:77], v71 offset0:4 offset1:6
	v_cvt_pk_bf16_f32 v217, v72, v73
	s_nop 1
	v_permlane32_swap_b32_e32 v214, v216
	v_permlane32_swap_b32_e32 v215, v217
	global_store_dwordx4 v[218:219], v[214:217], off offset:1248
	v_lshl_add_u64 v[72:73], s[16:17], 0, v[140:141]
	s_waitcnt lgkmcnt(1)
	v_mov_b32_e32 v70, v74
	s_waitcnt lgkmcnt(0)
; #define LAS __attribute__((address_space(3)))
; __device__ __forceinline__ unsigned pk2(float lo, float hi) { f32x2 v = {lo, hi}; bf16x2_t b = __builtin_convertvector(v, bf16x2_t); return __builtin_bit_cast(unsigned, b); }
; __device__ __forceinline__ void gmlp_unit(const GmlpP& P, int b, int ch, LAS unsigned char* lds, int wave, int lane_in) {
;     ...
;     for (int nt = 0; nt < 2; ++nt) {
;         const int t = 32 * (nt == 0 ? tt0 : tt1) + r32;
;         const float tot = (ssqg[t] + ssqg[128 + t]) + (ssqg[256 + t] + ssqg[384 + t]);
;         const float r = __builtin_amdgcn_rsqf(tot * (1.0f / GW) + EPS);
;         bf16_t* op = P.MIX + (tok0 + t) * DM + AW + gI * 128 + 4 * h;
; #pragma unroll
;         for (int mt = 0; mt < 4; ++mt)
; #pragma unroll
;             for (int e4 = 0; e4 < 4; ++e4) {
;                 const f32x4 gg = *(const LAS f32x4*)(lds + LDS_GG + (gI * 128 + 32 * mt + 8 * e4 + 4 * h) * 4);
;                 u32x2 w; w.x = pk2(acc[mt][nt][4 * e4] * r * gg[0], acc[mt][nt][4 * e4 + 1] * r * gg[1]); w.y = pk2(acc[mt][nt][4 * e4 + 2] * r * gg[2], acc[mt][nt][4 * e4 + 3] * r * gg[3]);
;                 *(u32x2*)(op + 32 * mt + 8 * e4) = w;
;             }
;     }
	v_mov_b32_e32 v71, v76
	v_mov_b32_e32 v76, v75
	v_pk_add_f32 v[70:71], v[70:71], v[76:77]
	v_lshl_add_u64 v[72:73], v[72:73], 0, v[150:151]
	v_add_f32_e32 v70, v70, v71
	v_fmamk_f32 v70, v70, 0x3b000000, v1
	v_rsq_f32_e32 v70, v70
	s_nop 0
	v_pk_mul_f32 v[64:65], v[64:65], v[70:71] op_sel_hi:[1,0]
	v_pk_mul_f32 v[62:63], v[62:63], v[70:71] op_sel_hi:[1,0]
	v_pk_mul_f32 v[6:7], v[6:7], v[64:65]
	v_pk_mul_f32 v[8:9], v[8:9], v[62:63]
	v_cvt_pk_bf16_f32 v202, v6, v7
	v_cvt_pk_bf16_f32 v203, v8, v9
	v_and_b32_e32 v222, 32, v0
	v_lshrrev_b32_e32 v222, 2, v222
	v_mov_b32_e32 v223, 0
	v_lshl_add_u64 v[220:221], v[72:73], 0, v[222:223]
	v_pk_mul_f32 v[6:7], v[60:61], v[70:71] op_sel_hi:[1,0]
	s_nop 0
	v_pk_mul_f32 v[2:3], v[2:3], v[6:7]
	v_pk_mul_f32 v[6:7], v[58:59], v[70:71] op_sel_hi:[1,0]
	v_cvt_pk_bf16_f32 v204, v2, v3
	v_pk_mul_f32 v[4:5], v[4:5], v[6:7]
	s_nop 0
	v_cvt_pk_bf16_f32 v205, v4, v5
	s_nop 1
	v_permlane32_swap_b32_e32 v202, v204
	v_permlane32_swap_b32_e32 v203, v205
	global_store_dwordx4 v[220:221], v[202:205], off offset:1024
	v_pk_mul_f32 v[2:3], v[56:57], v[70:71] op_sel_hi:[1,0]
	v_pk_mul_f32 v[4:5], v[54:55], v[70:71] op_sel_hi:[1,0]
	v_pk_mul_f32 v[2:3], v[10:11], v[2:3]
	v_pk_mul_f32 v[4:5], v[12:13], v[4:5]
	v_cvt_pk_bf16_f32 v206, v2, v3
	v_cvt_pk_bf16_f32 v207, v4, v5
	v_pk_mul_f32 v[2:3], v[52:53], v[70:71] op_sel_hi:[1,0]
	v_pk_mul_f32 v[4:5], v[50:51], v[70:71] op_sel_hi:[1,0]
	v_pk_mul_f32 v[2:3], v[114:115], v[2:3]
	v_pk_mul_f32 v[4:5], v[116:117], v[4:5]
	v_cvt_pk_bf16_f32 v208, v2, v3
	v_cvt_pk_bf16_f32 v209, v4, v5
	s_nop 1
	v_permlane32_swap_b32_e32 v206, v208
	v_permlane32_swap_b32_e32 v207, v209
	global_store_dwordx4 v[220:221], v[206:209], off offset:1056
	v_pk_mul_f32 v[2:3], v[36:37], v[70:71] op_sel_hi:[1,0]
	v_pk_mul_f32 v[4:5], v[34:35], v[70:71] op_sel_hi:[1,0]
	v_pk_mul_f32 v[2:3], v[118:119], v[2:3]
	v_pk_mul_f32 v[4:5], v[120:121], v[4:5]
	v_cvt_pk_bf16_f32 v210, v2, v3
	v_cvt_pk_bf16_f32 v211, v4, v5
	v_pk_mul_f32 v[2:3], v[38:39], v[70:71] op_sel_hi:[1,0]
	v_pk_mul_f32 v[4:5], v[40:41], v[70:71] op_sel_hi:[1,0]
	v_pk_mul_f32 v[2:3], v[122:123], v[2:3]
	v_pk_mul_f32 v[4:5], v[124:125], v[4:5]
	v_cvt_pk_bf16_f32 v212, v2, v3
	v_cvt_pk_bf16_f32 v213, v4, v5
	s_nop 1
	v_permlane32_swap_b32_e32 v210, v212
	v_permlane32_swap_b32_e32 v211, v213
	global_store_dwordx4 v[220:221], v[210:213], off offset:1088
	v_pk_mul_f32 v[2:3], v[42:43], v[70:71] op_sel_hi:[1,0]
	v_pk_mul_f32 v[4:5], v[44:45], v[70:71] op_sel_hi:[1,0]
	v_pk_mul_f32 v[2:3], v[98:99], v[2:3]
	v_pk_mul_f32 v[4:5], v[100:101], v[4:5]
	v_cvt_pk_bf16_f32 v214, v2, v3
	v_cvt_pk_bf16_f32 v215, v4, v5
	v_pk_mul_f32 v[2:3], v[46:47], v[70:71] op_sel_hi:[1,0]
	v_pk_mul_f32 v[4:5], v[48:49], v[70:71] op_sel_hi:[1,0]
	v_pk_mul_f32 v[2:3], v[126:127], v[2:3]
	v_pk_mul_f32 v[4:5], v[128:129], v[4:5]
	v_cvt_pk_bf16_f32 v216, v2, v3
	v_cvt_pk_bf16_f32 v217, v4, v5
	s_nop 1
	v_permlane32_swap_b32_e32 v214, v216
	v_permlane32_swap_b32_e32 v215, v217
	global_store_dwordx4 v[220:221], v[214:217], off offset:1120
	v_pk_mul_f32 v[2:3], v[18:19], v[70:71] op_sel_hi:[1,0]
	v_pk_mul_f32 v[4:5], v[20:21], v[70:71] op_sel_hi:[1,0]
	v_pk_mul_f32 v[2:3], v[102:103], v[2:3]
	v_pk_mul_f32 v[4:5], v[104:105], v[4:5]
	v_cvt_pk_bf16_f32 v202, v2, v3
	v_cvt_pk_bf16_f32 v203, v4, v5
	v_pk_mul_f32 v[2:3], v[22:23], v[70:71] op_sel_hi:[1,0]
	v_pk_mul_f32 v[4:5], v[24:25], v[70:71] op_sel_hi:[1,0]
	v_pk_mul_f32 v[2:3], v[106:107], v[2:3]
	v_pk_mul_f32 v[4:5], v[108:109], v[4:5]
	v_cvt_pk_bf16_f32 v204, v2, v3
	v_cvt_pk_bf16_f32 v205, v4, v5
	s_nop 1
	v_permlane32_swap_b32_e32 v202, v204
	v_permlane32_swap_b32_e32 v203, v205
	global_store_dwordx4 v[220:221], v[202:205], off offset:1152
	v_pk_mul_f32 v[2:3], v[26:27], v[70:71] op_sel_hi:[1,0]
	v_pk_mul_f32 v[4:5], v[28:29], v[70:71] op_sel_hi:[1,0]
	v_pk_mul_f32 v[2:3], v[82:83], v[2:3]
	v_pk_mul_f32 v[4:5], v[84:85], v[4:5]
	v_cvt_pk_bf16_f32 v206, v2, v3
	v_cvt_pk_bf16_f32 v207, v4, v5
	v_pk_mul_f32 v[2:3], v[30:31], v[70:71] op_sel_hi:[1,0]
	v_pk_mul_f32 v[4:5], v[32:33], v[70:71] op_sel_hi:[1,0]
	v_pk_mul_f32 v[2:3], v[110:111], v[2:3]
	v_pk_mul_f32 v[4:5], v[112:113], v[4:5]
	v_cvt_pk_bf16_f32 v208, v2, v3
	v_cvt_pk_bf16_f32 v209, v4, v5
	s_nop 1
	v_permlane32_swap_b32_e32 v206, v208
	v_permlane32_swap_b32_e32 v207, v209
	global_store_dwordx4 v[220:221], v[206:209], off offset:1184
	v_pk_mul_f32 v[2:3], v[80:81], v[70:71] op_sel_hi:[1,0]
	v_pk_mul_f32 v[4:5], v[132:133], v[70:71] op_sel_hi:[1,0]
	v_pk_mul_f32 v[2:3], v[86:87], v[2:3]
	v_pk_mul_f32 v[4:5], v[88:89], v[4:5]
	v_cvt_pk_bf16_f32 v210, v2, v3
	v_cvt_pk_bf16_f32 v211, v4, v5
	v_pk_mul_f32 v[2:3], v[134:135], v[70:71] op_sel_hi:[1,0]
	v_pk_mul_f32 v[4:5], v[136:137], v[70:71] op_sel_hi:[1,0]
	v_pk_mul_f32 v[2:3], v[90:91], v[2:3]
	v_pk_mul_f32 v[4:5], v[92:93], v[4:5]
	v_cvt_pk_bf16_f32 v212, v2, v3
	v_cvt_pk_bf16_f32 v213, v4, v5
	s_nop 1
	v_permlane32_swap_b32_e32 v210, v212
	v_permlane32_swap_b32_e32 v211, v213
	global_store_dwordx4 v[220:221], v[210:213], off offset:1216
	v_pk_mul_f32 v[2:3], v[146:147], v[70:71] op_sel_hi:[1,0]
	v_pk_mul_f32 v[4:5], v[148:149], v[70:71] op_sel_hi:[1,0]
	v_pk_mul_f32 v[2:3], v[66:67], v[2:3]
	v_pk_mul_f32 v[4:5], v[68:69], v[4:5]
	v_cvt_pk_bf16_f32 v214, v2, v3
	v_cvt_pk_bf16_f32 v215, v4, v5
	v_pk_mul_f32 v[2:3], v[14:15], v[70:71] op_sel_hi:[1,0]
	v_pk_mul_f32 v[4:5], v[16:17], v[70:71] op_sel_hi:[1,0]
	v_pk_mul_f32 v[2:3], v[94:95], v[2:3]
	v_pk_mul_f32 v[4:5], v[96:97], v[4:5]
	v_cvt_pk_bf16_f32 v216, v2, v3
	v_cvt_pk_bf16_f32 v217, v4, v5
	s_nop 1
	v_permlane32_swap_b32_e32 v214, v216
	v_permlane32_swap_b32_e32 v215, v217
	global_store_dwordx4 v[220:221], v[214:217], off offset:1248
	s_cbranch_scc1 .LBB0_545
